# combined: pipelined router LDS reads + batched modulation-vector loads (ln1_route) + batched LDS reads in the transposed-V copy-out (proj epilogue)
# speedup vs baseline: 1.0069x; 1.0069x over previous
.LBB0_203:
	v_cmp_ne_u32_e32 vcc, 2, v151
	s_andn2_b64 s[28:29], s[28:29], exec
	s_and_b64 vcc, vcc, exec
	s_or_b64 s[28:29], s[28:29], vcc
	s_andn2_b64 s[76:77], s[76:77], exec
	s_and_b64 vcc, s[46:47], exec
	s_or_b64 s[76:77], s[76:77], vcc
	s_or_b64 exec, exec, s[78:79]
	s_and_saveexec_b64 s[78:79], s[76:77]
	s_xor_b64 vcc, exec, s[78:79]
	s_cbranch_execz .LBB0_206
	s_and_b32 s20, s60, 0x780
	s_and_b64 s[76:77], s[88:89], exec
	s_cselect_b32 s20, s20, s59
	s_mov_b64 s[76:77], 0xe0
	s_andn2_b64 s[28:29], s[28:29], exec
	v_lshl_add_u64 v[128:129], s[20:21], 1, v[156:157]
	v_add_u32_e32 v221, 0x400, v199
	v_add_u32_e32 v222, 0x800, v199
	v_add_u32_e32 v234, 0xc00, v199
	ds_read2_b32 v[212:213], v199 offset1:132
	ds_read2_b32 v[214:215], v221 offset0:8 offset1:140
	ds_read2_b32 v[216:217], v222 offset0:16 offset1:148
	ds_read2_b32 v[218:219], v234 offset0:24 offset1:156
	s_waitcnt lgkmcnt(3)
	v_cvt_pk_bf16_f32 v130, v212, v213
	s_waitcnt lgkmcnt(2)
	v_cvt_pk_bf16_f32 v131, v214, v215
	s_waitcnt lgkmcnt(1)
	v_cvt_pk_bf16_f32 v132, v216, v217
	s_waitcnt lgkmcnt(0)
	v_cvt_pk_bf16_f32 v133, v218, v219
	global_store_dwordx4 v[128:129], v[130:133], off
	v_lshl_add_u64 v[164:165], v[128:129], 0, s[76:77]
	s_nop 0
	v_add_u32_e32 v220, 0x2000, v199
	v_add_u32_e32 v221, 0x2400, v199
	v_add_u32_e32 v222, 0x2800, v199
	v_add_u32_e32 v234, 0x2c00, v199
	ds_read2_b32 v[212:213], v220 offset0:64 offset1:196
	ds_read2_b32 v[214:215], v221 offset0:72 offset1:204
	ds_read2_b32 v[216:217], v222 offset0:80 offset1:212
	ds_read2_b32 v[218:219], v234 offset0:88 offset1:220
	s_waitcnt lgkmcnt(3)
	v_cvt_pk_bf16_f32 v130, v212, v213
	s_waitcnt lgkmcnt(2)
	v_cvt_pk_bf16_f32 v131, v214, v215
	s_waitcnt lgkmcnt(1)
	v_cvt_pk_bf16_f32 v132, v216, v217
	s_waitcnt lgkmcnt(0)
	v_cvt_pk_bf16_f32 v133, v218, v219
	global_store_dwordx4 v[128:129], v[130:133], off offset:32
	s_nop 1
	v_add_u32_e32 v220, 0x4200, v199
	v_add_u32_e32 v221, 0x4600, v199
	v_add_u32_e32 v222, 0x4a00, v199
	v_add_u32_e32 v234, 0x4e00, v199
	ds_read2_b32 v[212:213], v220 offset1:132
	ds_read2_b32 v[214:215], v221 offset0:8 offset1:140
	ds_read2_b32 v[216:217], v222 offset0:16 offset1:148
	ds_read2_b32 v[218:219], v234 offset0:24 offset1:156
	s_waitcnt lgkmcnt(3)
	v_cvt_pk_bf16_f32 v130, v212, v213
	s_waitcnt lgkmcnt(2)
	v_cvt_pk_bf16_f32 v131, v214, v215
	s_waitcnt lgkmcnt(1)
	v_cvt_pk_bf16_f32 v132, v216, v217
	s_waitcnt lgkmcnt(0)
	v_cvt_pk_bf16_f32 v133, v218, v219
	global_store_dwordx4 v[128:129], v[130:133], off offset:64
	s_nop 1
	v_add_u32_e32 v220, 0x6200, v199
	v_add_u32_e32 v221, 0x6600, v199
	v_add_u32_e32 v222, 0x6a00, v199
	v_add_u32_e32 v234, 0x6e00, v199
	ds_read2_b32 v[212:213], v220 offset0:64 offset1:196
	ds_read2_b32 v[214:215], v221 offset0:72 offset1:204
	ds_read2_b32 v[216:217], v222 offset0:80 offset1:212
	ds_read2_b32 v[218:219], v234 offset0:88 offset1:220
	s_waitcnt lgkmcnt(3)
	v_cvt_pk_bf16_f32 v130, v212, v213
	s_waitcnt lgkmcnt(2)
	v_cvt_pk_bf16_f32 v131, v214, v215
	s_waitcnt lgkmcnt(1)
	v_cvt_pk_bf16_f32 v132, v216, v217
	s_waitcnt lgkmcnt(0)
	v_cvt_pk_bf16_f32 v133, v218, v219
	global_store_dwordx4 v[128:129], v[130:133], off offset:96
	s_nop 1
	v_add_u32_e32 v220, 0x8400, v199
	v_add_u32_e32 v221, 0x8800, v199
	v_add_u32_e32 v222, 0x8c00, v199
	v_add_u32_e32 v234, 0x9000, v199
	ds_read2_b32 v[212:213], v220 offset1:132
	ds_read2_b32 v[214:215], v221 offset0:8 offset1:140
	ds_read2_b32 v[216:217], v222 offset0:16 offset1:148
	ds_read2_b32 v[218:219], v234 offset0:24 offset1:156
	s_waitcnt lgkmcnt(3)
	v_cvt_pk_bf16_f32 v130, v212, v213
	s_waitcnt lgkmcnt(2)
	v_cvt_pk_bf16_f32 v131, v214, v215
	s_waitcnt lgkmcnt(1)
	v_cvt_pk_bf16_f32 v132, v216, v217
	s_waitcnt lgkmcnt(0)
	v_cvt_pk_bf16_f32 v133, v218, v219
	global_store_dwordx4 v[128:129], v[130:133], off offset:128
	s_nop 1
	v_add_u32_e32 v220, 0xa400, v199
	v_add_u32_e32 v221, 0xa800, v199
	v_add_u32_e32 v222, 0xac00, v199
	v_add_u32_e32 v234, 0xb000, v199
	ds_read2_b32 v[212:213], v220 offset0:64 offset1:196
	ds_read2_b32 v[214:215], v221 offset0:72 offset1:204
	ds_read2_b32 v[216:217], v222 offset0:80 offset1:212
	ds_read2_b32 v[218:219], v234 offset0:88 offset1:220
	s_waitcnt lgkmcnt(3)
	v_cvt_pk_bf16_f32 v130, v212, v213
	s_waitcnt lgkmcnt(2)
	v_cvt_pk_bf16_f32 v131, v214, v215
	s_waitcnt lgkmcnt(1)
	v_cvt_pk_bf16_f32 v132, v216, v217
	s_waitcnt lgkmcnt(0)
	v_cvt_pk_bf16_f32 v133, v218, v219
	global_store_dwordx4 v[128:129], v[130:133], off offset:160
	s_nop 1
	v_add_u32_e32 v220, 0xc600, v199
	v_add_u32_e32 v221, 0xca00, v199
	v_add_u32_e32 v222, 0xce00, v199
	v_add_u32_e32 v234, 0xd200, v199
	ds_read2_b32 v[212:213], v220 offset1:132
	ds_read2_b32 v[214:215], v221 offset0:8 offset1:140
	ds_read2_b32 v[216:217], v222 offset0:16 offset1:148
	ds_read2_b32 v[218:219], v234 offset0:24 offset1:156
	s_waitcnt lgkmcnt(3)
	v_cvt_pk_bf16_f32 v130, v212, v213
	s_waitcnt lgkmcnt(2)
	v_cvt_pk_bf16_f32 v131, v214, v215
	s_waitcnt lgkmcnt(1)
	v_cvt_pk_bf16_f32 v132, v216, v217
	s_waitcnt lgkmcnt(0)
	v_cvt_pk_bf16_f32 v133, v218, v219
	global_store_dwordx4 v[128:129], v[130:133], off offset:192
	v_add_u32_e32 v134, 0xf200, v199
	ds_read2_b32 v[134:135], v134 offset0:88 offset1:220
	v_add_u32_e32 v130, 0xe600, v199
	ds_read2_b32 v[130:131], v130 offset0:64 offset1:196
	v_add_u32_e32 v132, 0xee00, v199
	ds_read2_b32 v[132:133], v132 offset0:80 offset1:212
	s_waitcnt lgkmcnt(1)
	v_cvt_pk_bf16_f32 v139, v130, v131
	v_add_u32_e32 v130, 0xea00, v199
	ds_read2_b32 v[130:131], v130 offset0:72 offset1:204
	global_store_dword v[128:129], v139, off offset:224
